# attention units dealt per XCD (8 ticket counters; unit = G + 8*ticket + bid%8) so a (batch, head-pair)'s K/V stays in one XCD's L2 (on top of v029)
# speedup vs baseline: 1.0108x; 1.0039x over previous
; #define DEAL_LOOP(F, ctr, N, BODY) do { gu32* _c = (ctr); int u = F.bid; while (u < (N)) { const unsigned _t = deal_prefetch(F, _c); BODY; u = deal_publish(F, _t) + F.G; } __syncthreads(); } while (0)
; #define REPBAR(k) do { if (rep + 1 < REPS(k)) xcd_barrier(bar); } while (0)
; #define LAUNDER() do { launder(F); GAS unsigned char* _g = (GAS unsigned char*)ws; asm volatile("" : "+s"(_g)); ws = (unsigned char*)_g; } while (0)
; __global__ void __launch_bounds__(NTHR, 2) fwd(Args args) {
;     ...
;             for (int rep = 0; rep < REPS(8); ++rep) { LAUNDER();
;                 if (PH_ON(8)) DEAL_LOOP(F, cnt_word(F, l, CNT_ATTN + 5 * rep), AT_UNITS, attn_unit<0>(args, F, l, u));
;                 REPBAR(8); }
.LBB0_1366:
	s_or_b64 exec, exec, s[2:3]
	s_lshl_b32 s4, s90, 10
	v_readlane_b32 s0, v249, 25
	s_add_u32 s0, s74, s0
	s_mov_b32 s5, s63
	v_writelane_b32 v249, s0, 31
	s_addc_u32 s0, s75, 0
	s_cmpk_lt_i32 s69, 0x240
	v_cmp_eq_u32_e64 s[36:37], 0, v0
	v_writelane_b32 v249, s0, 32
	s_cbranch_scc0 .LBB0_1420
	s_lshl_b64 s[0:1], s[4:5], 2
	s_add_u32 s0, s74, s0
	s_addc_u32 s1, s75, s1
	s_add_u32 s6, s0, 0x10c00
	s_addc_u32 s7, s1, 0
	s_and_b32 s101, s69, 7
	s_lshl_b32 s101, s101, 7
	s_add_u32 s6, s6, s101
	s_addc_u32 s7, s7, 0
	v_readlane_b32 s2, v249, 31
	s_add_u32 s8, s2, 0x3b86000
	v_readlane_b32 s3, v249, 32
	v_readlane_b32 s12, v250, 60
	s_addc_u32 s9, s3, 0
	s_lshl_b32 s62, s90, 6
	v_readlane_b32 s22, v251, 6
	v_readlane_b32 s23, v251, 7
	v_readlane_b32 s26, v251, 10
	v_readlane_b32 s27, v251, 11
	s_lshl_b32 s33, s90, 24
	s_lshl_b64 s[0:1], s[62:63], 2
	s_mov_b64 s[22:23], s[26:27]
	s_add_u32 s10, s22, s0
	s_addc_u32 s11, s23, s1
	v_readlane_b32 s13, v250, 61
	v_readlane_b32 s20, v251, 4
	s_add_u32 s12, s2, 0x3b86004
	s_addc_u32 s13, s3, 0
	s_mov_b32 s20, s69
	v_readlane_b32 s14, v250, 62
	v_readlane_b32 s15, v250, 63
	v_readlane_b32 s16, v251, 0
	v_readlane_b32 s17, v251, 1
	v_readlane_b32 s18, v251, 2
	v_readlane_b32 s19, v251, 3
	v_readlane_b32 s21, v251, 5
	v_readlane_b32 s24, v251, 8
	v_readlane_b32 s25, v251, 9
	s_branch .LBB0_1369
.LBB0_1368:
	s_or_b64 exec, exec, s[0:1]
	v_mov_b32_e32 v3, s79
	s_waitcnt lgkmcnt(0)
	s_barrier
	ds_read_b32 v3, v3
	s_waitcnt lgkmcnt(0)
	v_readfirstlane_b32 s0, v3
	s_lshl_b32 s0, s0, 3
	s_add_i32 s20, s0, s76
	s_and_b32 s101, s69, 7
	s_add_i32 s20, s20, s101
	s_cmpk_lt_i32 s20, 0x240
	s_cbranch_scc0 .LBB0_1420
